# GQA and MLA-partial barrier zones reordered: LDS writes issued right after the post-barrier vmcnt wait, exps after; address chain hoisted before the barrier
# speedup vs baseline: 1.0042x; 1.0042x over previous
; #define WAIT_V0() asm volatile("s_waitcnt vmcnt(0)" ::: "memory")
; #define SBAR() __builtin_amdgcn_sched_barrier(0)
; #define SWRITE(b) do { FRESH_COORDS(); \
;     if constexpr (!KDMA) { _Pragma("unroll") for (int i = 0; i < KC; ++i) *reinterpret_cast<bf16x8*>(shm + (b) * SHM_K + klo[i]) = ks[i]; } \
;     _Pragma("unroll") for (int i = 0; i < VC; ++i) *reinterpret_cast<bf16x8*>(shm + (b) * SHM_V + vlo[i]) = vs[i]; } while (0)
; #define QKT(P0, P1, BUF) qkt<DQK, QL>(P0, P1, shm + K_OFF + (BUF) * SHM_K, qr, qlds, kofs, negM)
; __device__ __forceinline__ void finishSM(f32x16& p0, f32x16& p1, float& l_reg, bf16x8& pa0, bf16x8& pa1, bf16x8& pa2, bf16x8& pa3) {
; #pragma unroll
;   for (int r = 0; r < 16; ++r) p1[r] = __builtin_amdgcn_exp2f(p1[r]);
;   float ps = 0;
; #pragma unroll
;   for (int r = 0; r < 16; ++r) ps += p0[r];
; #pragma unroll
;   for (int r = 0; r < 16; ++r) ps += p1[r];
;   { auto rr = __builtin_amdgcn_permlane32_swap(__float_as_uint(ps), __float_as_uint(ps), false, false);
;     ps = __uint_as_float(rr[0]) + __uint_as_float(rr[1]); }
;   l_reg += ps;
;     ...
;   PK4(p0, 0, pa0); PK4(p0, 8, pa1); PK4(p1, 0, pa2); PK4(p1, 8, pa3);
;     ...
; }
; template <int DQK, int QL>
; __device__ __forceinline__ void qkt(f32x16& p0, f32x16& p1, const char* Ks, const bf16x8 (&qr)[DQK / 16 - QL], const char* qlds, const int (&kofs)[4], float negM) {
;   constexpr int QR = DQK / 16 - QL;
; #pragma unroll
;   for (int r = 0; r < 16; ++r) { p0[r] = negM; p1[r] = negM; }
; #pragma unroll
;   for (int d0 = 0; d0 < DQK / 16; ++d0) {
;     const char* kp = Ks + kofs[d0 & 3] + (d0 >> 2) * 128;
;     bf16x8 b0 = *reinterpret_cast<const bf16x8*>(kp);
;     bf16x8 b1 = *reinterpret_cast<const bf16x8*>(kp + 32 * DQK * 2);
;     bf16x8 qf;
;     if constexpr (QL > 0) { if (d0 < QR) qf = qr[d0 < QR ? d0 : 0]; else qf = *reinterpret_cast<const bf16x8*>(qlds + (d0 - QR) * 1024); }
;     else qf = qr[d0];
;     p0 = __builtin_amdgcn_mfma_f32_32x32x16_bf16(b0, qf, p0, 0, 0, 0);
;     p1 = __builtin_amdgcn_mfma_f32_32x32x16_bf16(b1, qf, p1, 0, 0, 0);
;   }
;     ...
;     __syncthreads(); WAIT_V0(); SWRITE(0);
;     __syncthreads();
;     SBAR();
;     if constexpr (ONEP) { finishSM(pB0, pB1, l_reg, pa0, pa1, pa2, pa3); SBAR(); QKT(pA0, pA1, 0); }
;     else { QKT(pA0, pA1, 0); finishSM(pB0, pB1, l_reg, pa0, pa1, pa2, pa3); }
.LBB0_432:
	v_mov_b32_e32 v96, v157
	v_ashrrev_i32_e32 v97, 4, v96
	v_and_b32_e32 v99, 0xfffff0, v97
	v_lshlrev_b32_e32 v100, 1, v97
	v_add_u32_e32 v98, 32, v97
	v_and_or_b32 v99, v100, 8, v99
	v_lshrrev_b32_e32 v100, 1, v97
	v_and_b32_e32 v97, 3, v97
	v_and_or_b32 v97, v100, 4, v97
	v_and_b32_e32 v100, 0xfffff0, v98
	v_lshlrev_b32_e32 v98, 1, v98
	v_and_or_b32 v98, v98, 8, v100
	v_lshrrev_b32_e32 v99, 1, v99
	v_bfe_u32 v101, v96, 2, 2
	v_lshrrev_b32_e32 v98, 1, v98
	v_or_b32_e32 v99, v99, v101
	v_lshlrev_b32_e32 v96, 4, v96
	v_or_b32_e32 v98, v98, v101
	v_lshlrev_b32_e32 v99, 9, v99
	v_lshlrev_b32_e32 v97, 6, v97
	v_and_b32_e32 v96, 48, v96
	v_lshlrev_b32_e32 v98, 9, v98
	v_or3_b32 v99, v99, v97, v96
	v_or3_b32 v96, v98, v97, v96
	s_waitcnt vmcnt(0)
	s_barrier
	s_waitcnt vmcnt(0)
	ds_write_b128 v99, v[130:133]
	ds_write_b128 v96, v[124:127]
	v_exp_f32_e32 v64, v64
	v_exp_f32_e32 v66, v66
	v_exp_f32_e32 v68, v68
	v_exp_f32_e32 v70, v70
	v_exp_f32_e32 v72, v72
	v_exp_f32_e32 v74, v74
	v_exp_f32_e32 v76, v76
	v_exp_f32_e32 v78, v78
	v_exp_f32_e32 v65, v65
	v_exp_f32_e32 v67, v67
	v_exp_f32_e32 v69, v69
	v_exp_f32_e32 v71, v71
	v_exp_f32_e32 v73, v73
	v_exp_f32_e32 v75, v75
	v_exp_f32_e32 v77, v77
	v_exp_f32_e32 v79, v79
	s_waitcnt lgkmcnt(0)
	s_barrier
	v_add_f32_e32 v96, 0, v64
	v_add_f32_e32 v96, v65, v96
	v_add_f32_e32 v96, v66, v96
	v_add_f32_e32 v96, v67, v96
	v_add_f32_e32 v96, v68, v96
	v_add_f32_e32 v96, v69, v96
	v_add_f32_e32 v96, v70, v96
	v_add_f32_e32 v96, v71, v96
	v_add_f32_e32 v96, v72, v96
	v_add_f32_e32 v96, v73, v96
	v_add_f32_e32 v96, v74, v96
	v_add_f32_e32 v96, v75, v96
	v_exp_f32_e32 v80, v80
	v_add_f32_e32 v96, v76, v96
	v_exp_f32_e32 v81, v81
	v_add_f32_e32 v96, v77, v96
	v_exp_f32_e32 v82, v82
	v_add_f32_e32 v96, v78, v96
	v_exp_f32_e32 v83, v83
	v_add_f32_e32 v96, v79, v96
	v_exp_f32_e32 v84, v84
	v_add_f32_e32 v96, v80, v96
	v_exp_f32_e32 v85, v85
	v_add_f32_e32 v96, v81, v96
	v_exp_f32_e32 v86, v86
	v_add_f32_e32 v96, v82, v96
	v_exp_f32_e32 v87, v87
	v_add_f32_e32 v96, v83, v96
	v_exp_f32_e32 v88, v88
	v_add_f32_e32 v96, v84, v96
	v_exp_f32_e32 v89, v89
	v_add_f32_e32 v96, v85, v96
	v_exp_f32_e32 v90, v90
	v_add_f32_e32 v96, v86, v96
	v_exp_f32_e32 v91, v91
	v_add_f32_e32 v96, v87, v96
	v_exp_f32_e32 v92, v92
	v_add_f32_e32 v96, v88, v96
	v_exp_f32_e32 v93, v93
	v_add_f32_e32 v96, v89, v96
	v_exp_f32_e32 v94, v94
	v_add_f32_e32 v96, v90, v96
	v_exp_f32_e32 v95, v95
	v_add_f32_e32 v96, v91, v96
	v_add_f32_e32 v96, v92, v96
	v_add_f32_e32 v96, v93, v96
	v_add_f32_e32 v96, v94, v96
	v_add_f32_e32 v172, v95, v96
	v_mov_b32_e32 v173, v172
	v_cvt_pk_bf16_f32 v134, v64, v65
	v_cvt_pk_bf16_f32 v135, v66, v67
	v_cvt_pk_bf16_f32 v136, v68, v69
	v_cvt_pk_bf16_f32 v137, v70, v71
	v_cvt_pk_bf16_f32 v138, v72, v73
	v_cvt_pk_bf16_f32 v139, v74, v75
	v_cvt_pk_bf16_f32 v140, v76, v77
	v_cvt_pk_bf16_f32 v141, v78, v79
	v_cvt_pk_bf16_f32 v142, v80, v81
	v_cvt_pk_bf16_f32 v143, v82, v83
	v_cvt_pk_bf16_f32 v144, v84, v85
	v_cvt_pk_bf16_f32 v145, v86, v87
	v_cvt_pk_bf16_f32 v146, v88, v89
	v_cvt_pk_bf16_f32 v147, v90, v91
	v_cvt_pk_bf16_f32 v148, v92, v93
	v_cvt_pk_bf16_f32 v149, v94, v95
	s_nop 1
	v_permlane32_swap_b32_e32 v172, v173
	v_permlane32_swap_b32_e32 v134, v136
	v_permlane32_swap_b32_e32 v135, v137
	v_permlane32_swap_b32_e32 v138, v140
	v_permlane32_swap_b32_e32 v139, v141
	v_permlane32_swap_b32_e32 v142, v144
	v_permlane32_swap_b32_e32 v143, v145
	v_permlane32_swap_b32_e32 v146, v148
	v_permlane32_swap_b32_e32 v147, v149
	ds_read_b128 v[64:67], v153 offset:32768
	ds_read_b128 v[174:177], v153 offset:45056
	v_mov_b64_e32 v[110:111], s[18:19]
	v_mov_b64_e32 v[108:109], s[16:17]
	v_mov_b64_e32 v[106:107], s[14:15]
	v_mov_b64_e32 v[104:105], s[12:13]
	v_mov_b64_e32 v[102:103], s[10:11]
	v_mov_b64_e32 v[100:101], s[8:9]
	v_mov_b64_e32 v[98:99], s[6:7]
	v_mov_b64_e32 v[96:97], s[4:5]
	s_waitcnt lgkmcnt(1)
	s_nop 0
	v_mfma_f32_32x32x16_bf16 v[80:95], v[64:67], v[120:123], v[96:111]
	s_waitcnt lgkmcnt(0)
	v_mfma_f32_32x32x16_bf16 v[64:79], v[174:177], v[120:123], v[96:111]
	s_nop 6
	ds_read_b128 v[96:99], v152 offset:32768
	ds_read_b128 v[100:103], v152 offset:45056
	s_waitcnt lgkmcnt(1)
	v_mfma_f32_32x32x16_bf16 v[80:95], v[96:99], v[116:119], v[80:95]
	s_waitcnt lgkmcnt(0)
	v_mfma_f32_32x32x16_bf16 v[64:79], v[100:103], v[116:119], v[64:79]
	ds_read_b128 v[96:99], v151 offset:32768
	ds_read_b128 v[100:103], v151 offset:45056
	s_waitcnt lgkmcnt(1)
	v_mfma_f32_32x32x16_bf16 v[80:95], v[96:99], v[112:115], v[80:95]
	s_waitcnt lgkmcnt(0)
	v_mfma_f32_32x32x16_bf16 v[64:79], v[100:103], v[112:115], v[64:79]
	ds_read_b128 v[96:99], v150 offset:32768
	ds_read_b128 v[100:103], v150 offset:45056
	ds_read_b128 v[104:107], v171
	s_waitcnt lgkmcnt(0)
; __device__ __forceinline__ int v_rd_base(int lane) { return ((lane & 3) << 3) | (((lane >> 2) & 3) << 6) | (((lane >> 4) & 1) << 5) | (((lane >> 5) & 1) << 8); }
; #define V_COORDS(T) do { if constexpr (VC == 2) { const int sr = (T) >> 4, sc = ((T) & 15) * 8; vgo[0] = sr * LDV + sc; vgo[VC - 1] = (32 + sr) * LDV + sc; vlo[0] = v_st<NCB>(sr, sc); vlo[VC - 1] = v_st<NCB>(32 + sr, sc); } \
;     else { const int sr = (T) >> 3, sc = ((T) & 7) * 8; vgo[0] = sr * LDV + sc; vlo[0] = v_st<NCB>(sr, sc); } } while (0)
; template <int DQK, int QL>
; __device__ __forceinline__ void qkt(f32x16& p0, f32x16& p1, const char* Ks, const bf16x8 (&qr)[DQK / 16 - QL], const char* qlds, const int (&kofs)[4], float negM) {
;     ...
;   for (int d0 = 0; d0 < DQK / 16; ++d0) {
;     const char* kp = Ks + kofs[d0 & 3] + (d0 >> 2) * 128;
;     bf16x8 b0 = *reinterpret_cast<const bf16x8*>(kp);
;     bf16x8 b1 = *reinterpret_cast<const bf16x8*>(kp + 32 * DQK * 2);
;     bf16x8 qf;
;     if constexpr (QL > 0) { if (d0 < QR) qf = qr[d0 < QR ? d0 : 0]; else qf = *reinterpret_cast<const bf16x8*>(qlds + (d0 - QR) * 1024); }
;     else qf = qr[d0];
;     p0 = __builtin_amdgcn_mfma_f32_32x32x16_bf16(b0, qf, p0, 0, 0, 0);
;     p1 = __builtin_amdgcn_mfma_f32_32x32x16_bf16(b1, qf, p1, 0, 0, 0);
;   }
;     ...
;   if constexpr (KDMA) {
;   } else {
; #pragma unroll
;     for (int i = 0; i < KC; ++i) { const int c = tid + i * 512, row = c / CPR, cc = c % CPR; kgo[i] = row * LDK + cc * 8; klo[i] = K_OFF + KSWZ(KRS, row, cc * 16); }
;     V_COORDS(tid);
;   }
;   const int vb0 = (int)(uintptr_t)shm + v_rd_base(lane);
;   int kofs[4];
; #pragma unroll
;   for (int b = 0; b < 4; ++b) kofs[b] = (r32 ^ ((r32 >> 3) & 1)) * KRS + ((b * 32 + hi * 16) ^ ((r32 & 7) << 4));
;   bf16x8 ks[KC], vs[VC];
	v_mfma_f32_32x32x16_bf16 v[80:95], v[96:99], v[104:107], v[80:95]
	v_mfma_f32_32x32x16_bf16 v[64:79], v[100:103], v[104:107], v[64:79]
	ds_read_b128 v[96:99], v153 offset:32896
	ds_read_b128 v[100:103], v153 offset:45184
	ds_read_b128 v[104:107], v171 offset:1024
	s_waitcnt lgkmcnt(0)
	v_mfma_f32_32x32x16_bf16 v[80:95], v[96:99], v[104:107], v[80:95]
	v_mfma_f32_32x32x16_bf16 v[64:79], v[100:103], v[104:107], v[64:79]
	ds_read_b128 v[96:99], v152 offset:32896
	ds_read_b128 v[100:103], v152 offset:45184
	ds_read_b128 v[104:107], v171 offset:2048
	s_waitcnt lgkmcnt(0)
	v_mfma_f32_32x32x16_bf16 v[80:95], v[96:99], v[104:107], v[80:95]
	v_mfma_f32_32x32x16_bf16 v[64:79], v[100:103], v[104:107], v[64:79]
	ds_read_b128 v[96:99], v151 offset:32896
	ds_read_b128 v[100:103], v151 offset:45184
	ds_read_b128 v[104:107], v171 offset:3072
	s_waitcnt lgkmcnt(0)
	v_mfma_f32_32x32x16_bf16 v[80:95], v[96:99], v[104:107], v[80:95]
	v_mfma_f32_32x32x16_bf16 v[64:79], v[100:103], v[104:107], v[64:79]
	ds_read_b128 v[96:99], v150 offset:32896
	ds_read_b128 v[100:103], v150 offset:45184
	ds_read_b128 v[104:107], v171 offset:4096
	s_waitcnt lgkmcnt(0)
	v_mfma_f32_32x32x16_bf16 v[80:95], v[96:99], v[104:107], v[80:95]
	v_mfma_f32_32x32x16_bf16 v[64:79], v[100:103], v[104:107], v[64:79]
	ds_read_b128 v[96:99], v153 offset:33024
	ds_read_b128 v[100:103], v153 offset:45312
	ds_read_b128 v[104:107], v171 offset:5120
	s_waitcnt lgkmcnt(0)
	v_mfma_f32_32x32x16_bf16 v[80:95], v[96:99], v[104:107], v[80:95]
	v_mfma_f32_32x32x16_bf16 v[64:79], v[100:103], v[104:107], v[64:79]
	ds_read_b128 v[96:99], v152 offset:33024
	ds_read_b128 v[100:103], v152 offset:45312
	ds_read_b128 v[104:107], v171 offset:6144
	s_waitcnt lgkmcnt(0)
	v_mfma_f32_32x32x16_bf16 v[80:95], v[96:99], v[104:107], v[80:95]
	v_mfma_f32_32x32x16_bf16 v[64:79], v[100:103], v[104:107], v[64:79]
	ds_read_b128 v[96:99], v151 offset:33024
	ds_read_b128 v[100:103], v151 offset:45312
	ds_read_b128 v[104:107], v171 offset:7168
	s_waitcnt lgkmcnt(0)
	v_mfma_f32_32x32x16_bf16 v[80:95], v[96:99], v[104:107], v[80:95]
	v_mfma_f32_32x32x16_bf16 v[64:79], v[100:103], v[104:107], v[64:79]
	ds_read_b128 v[96:99], v150 offset:33024
	ds_read_b128 v[100:103], v150 offset:45312
	ds_read_b128 v[104:107], v171 offset:8192
	s_waitcnt lgkmcnt(0)
	v_mfma_f32_32x32x16_bf16 v[80:95], v[96:99], v[104:107], v[80:95]
	v_mfma_f32_32x32x16_bf16 v[64:79], v[100:103], v[104:107], v[64:79]
	s_cmp_lt_i32 s22, s54
	s_cselect_b64 s[20:21], -1, 0
	s_cmp_ge_i32 s22, s54
	s_cbranch_scc1 .LBB0_434
	v_mov_b32_e32 v97, v157
	s_add_i32 vcc_lo, s23, 0xc0
	v_mul_hi_i32 v99, v97, s82
	v_lshrrev_b32_e32 v100, 31, v99
	v_ashrrev_i32_e32 v99, 2, v99
	v_add_u32_e32 v99, v99, v100
	v_mul_lo_u32 v100, v99, 24
	v_lshrrev_b32_e32 v101, 3, v99
	v_sub_u32_e32 v100, v97, v100
	v_bitop3_b32 v99, v101, v99, 1 bitop3:0x6c
	v_bitop3_b32 v100, v99, v100, 7 bitop3:0x6c
	v_mul_lo_u32 v99, v99, s85
	v_lshl_add_u32 v100, v100, 3, v99
	v_add_u32_e32 v99, 0x200, v97
	v_mul_hi_i32 v101, v99, s82
	v_lshrrev_b32_e32 v102, 31, v101
	v_ashrrev_i32_e32 v101, 2, v101
	v_add_u32_e32 v101, v101, v102
	v_mul_lo_u32 v102, v101, 24
	v_sub_u32_e32 v99, v99, v102
	v_lshrrev_b32_e32 v102, 3, v101
	v_bitop3_b32 v101, v102, v101, 1 bitop3:0x6c
	v_lshlrev_b32_e32 v96, 3, v97
	v_lshlrev_b32_e32 v98, 5, v97
	v_bitop3_b32 v99, v101, v99, 7 bitop3:0x6c
	v_mul_lo_u32 v101, v101, s85
	v_add_u32_e32 v97, 0x400, v97
	v_lshl_add_u32 v102, v99, 3, v101
	v_mul_hi_i32 v99, v97, s82
	v_lshrrev_b32_e32 v101, 31, v99
	v_ashrrev_i32_e32 v99, 2, v99
	v_add_u32_e32 v99, v99, v101
	v_mul_lo_u32 v101, v99, 24
	v_sub_u32_e32 v97, v97, v101
	v_lshrrev_b32_e32 v101, 3, v99
	v_bitop3_b32 v99, v101, v99, 1 bitop3:0x6c
	s_ashr_i32 vcc_hi, vcc_lo, 31
	s_mul_i32 s38, vcc_lo, 0x600
	v_bitop3_b32 v97, v99, v97, 7 bitop3:0x6c
	v_mul_lo_u32 v99, v99, s85
	s_mul_hi_i32 s23, vcc_lo, 0x600
	s_add_u32 s38, s3, s38
	v_lshl_add_u32 v104, v97, 3, v99
	s_addc_u32 s39, s36, s23
	v_ashrrev_i32_e32 v101, 31, v100
	v_readfirstlane_b32 s23, v167
	v_add_u32_e32 v97, 0x2000, v167
	v_lshl_add_u64 v[100:101], v[100:101], 1, s[38:39]
	s_mov_b32 m0, s23
	v_ashrrev_i32_e32 v103, 31, v102
	v_readfirstlane_b32 s23, v97
	global_load_lds_dwordx4 v[100:101], off
	v_lshl_add_u64 v[100:101], v[102:103], 1, s[38:39]
	s_mov_b32 m0, s23
	v_ashrrev_i32_e32 v105, 31, v104
	v_and_b32_e32 v96, 0x78, v96
	global_load_lds_dwordx4 v[100:101], off
	v_lshl_add_u64 v[100:101], v[104:105], 1, s[38:39]
	v_add_u32_e32 v97, 0x4000, v167
	s_lshl_b64 s[38:39], vcc, 10
	v_and_or_b32 v96, v98, s24, v96
	v_readfirstlane_b32 s23, v97
	s_add_u32 s38, s83, s38
	v_add_u32_e32 v98, 0x4000, v96
	s_mov_b32 m0, s23
	s_addc_u32 s39, s93, s39
	v_ashrrev_i32_e32 v97, 31, v96
	global_load_lds_dwordx4 v[100:101], off
	v_lshl_add_u64 v[96:97], v[96:97], 1, s[38:39]
	v_ashrrev_i32_e32 v99, 31, v98
	v_lshl_add_u64 v[98:99], v[98:99], 1, s[38:39]
	global_load_dwordx4 v[130:133], v[96:97], off
	global_load_dwordx4 v[124:127], v[98:99], off

; #define WAIT_V0() asm volatile("s_waitcnt vmcnt(0)" ::: "memory")
; #define SWRITE(b) do { FRESH_COORDS(); \
;     if constexpr (!KDMA) { _Pragma("unroll") for (int i = 0; i < KC; ++i) *reinterpret_cast<bf16x8*>(shm + (b) * SHM_K + klo[i]) = ks[i]; } \
;     _Pragma("unroll") for (int i = 0; i < VC; ++i) *reinterpret_cast<bf16x8*>(shm + (b) * SHM_V + vlo[i]) = vs[i]; } while (0)
;     ...
;     __syncthreads();
;     if (j + 2 < NT) { WAIT_V0(); SWRITE(1); }
;     __syncthreads();
.LBB0_436:
	v_mov_b32_e32 v96, v157
	v_ashrrev_i32_e32 v97, 4, v96
	v_and_b32_e32 v99, 0xfffff0, v97
	v_lshlrev_b32_e32 v100, 1, v97
	v_add_u32_e32 v98, 32, v97
	v_and_or_b32 v99, v100, 8, v99
	v_lshrrev_b32_e32 v100, 1, v97
	v_and_b32_e32 v97, 3, v97
	v_and_or_b32 v97, v100, 4, v97
	v_and_b32_e32 v100, 0xfffff0, v98
	v_lshlrev_b32_e32 v98, 1, v98
	v_and_or_b32 v98, v98, 8, v100
	v_lshrrev_b32_e32 v99, 1, v99
	v_bfe_u32 v101, v96, 2, 2
	v_lshrrev_b32_e32 v98, 1, v98
	v_or_b32_e32 v99, v99, v101
	v_lshlrev_b32_e32 v96, 4, v96
	v_or_b32_e32 v98, v98, v101
	v_lshlrev_b32_e32 v99, 9, v99
	v_lshlrev_b32_e32 v97, 6, v97
	v_and_b32_e32 v96, 48, v96
	v_lshlrev_b32_e32 v98, 9, v98
	v_or3_b32 v99, v99, v97, v96
	v_or3_b32 v96, v98, v97, v96
	s_andn2_b64 vcc, exec, s[20:21]
	s_waitcnt vmcnt(0) lgkmcnt(0)
	s_barrier
	s_cbranch_vccnz .LBB0_438
	s_waitcnt vmcnt(0)
	ds_write_b128 v99, v[130:133] offset:16384
	ds_write_b128 v96, v[124:127] offset:16384

; #define WAIT_V0() asm volatile("s_waitcnt vmcnt(0)" ::: "memory")
; #define SBAR() __builtin_amdgcn_sched_barrier(0)
; #define QKT(P0, P1, BUF) qkt<DQK, QL>(P0, P1, shm + K_OFF + (BUF) * SHM_K, qr, qlds, kofs, negM)
; template <bool GM>
; __device__ __forceinline__ void partialSM(f32x16& p0, f32x16& p1, bool mask, int kbase, int L, int qpos, int hi) {
;     ...
;   for (int r = 0; r < 16; ++r) p0[r] = __builtin_amdgcn_exp2f(p0[r]);
; }
; __device__ __forceinline__ void finishSM(f32x16& p0, f32x16& p1, float& l_reg, bf16x8& pa0, bf16x8& pa1, bf16x8& pa2, bf16x8& pa3) {
; #pragma unroll
;   for (int r = 0; r < 16; ++r) p1[r] = __builtin_amdgcn_exp2f(p1[r]);
;   float ps = 0;
; #pragma unroll
;   for (int r = 0; r < 16; ++r) ps += p0[r];
; #pragma unroll
;   for (int r = 0; r < 16; ++r) ps += p1[r];
;   { auto rr = __builtin_amdgcn_permlane32_swap(__float_as_uint(ps), __float_as_uint(ps), false, false);
;     ps = __uint_as_float(rr[0]) + __uint_as_float(rr[1]); }
;   l_reg += ps;
;     ...
;   PK4(p0, 0, pa0); PK4(p0, 8, pa1); PK4(p1, 0, pa2); PK4(p1, 8, pa3);
;     ...
; }
; template <int DQK, int QL>
; __device__ __forceinline__ void qkt(f32x16& p0, f32x16& p1, const char* Ks, const bf16x8 (&qr)[DQK / 16 - QL], const char* qlds, const int (&kofs)[4], float negM) {
;   constexpr int QR = DQK / 16 - QL;
; #pragma unroll
;   for (int r = 0; r < 16; ++r) { p0[r] = negM; p1[r] = negM; }
; #pragma unroll
;   for (int d0 = 0; d0 < DQK / 16; ++d0) {
;     const char* kp = Ks + kofs[d0 & 3] + (d0 >> 2) * 128;
;     bf16x8 b0 = *reinterpret_cast<const bf16x8*>(kp);
;     bf16x8 b1 = *reinterpret_cast<const bf16x8*>(kp + 32 * DQK * 2);
;     bf16x8 qf;
;     if constexpr (QL > 0) { if (d0 < QR) qf = qr[d0 < QR ? d0 : 0]; else qf = *reinterpret_cast<const bf16x8*>(qlds + (d0 - QR) * 1024); }
;     else qf = qr[d0];
;     p0 = __builtin_amdgcn_mfma_f32_32x32x16_bf16(b0, qf, p0, 0, 0, 0);
;     p1 = __builtin_amdgcn_mfma_f32_32x32x16_bf16(b1, qf, p1, 0, 0, 0);
;   }
;     ...
;     __syncthreads(); WAIT_V0(); SWRITE(0);
;     __syncthreads();
;     SBAR();
;     if constexpr (ONEP) { finishSM(pB0, pB1, l_reg, pa0, pa1, pa2, pa3); SBAR(); QKT(pA0, pA1, 0); }
;     else { QKT(pA0, pA1, 0); finishSM(pB0, pB1, l_reg, pa0, pa1, pa2, pa3); }
;     SBAR();
;     if (j + 2 < NT) SLOAD(TKEY(j + 2), 1);
.Lgq_end_1:
	s_barrier
	s_waitcnt vmcnt(0)
	ds_write_b128 v154, v[96:99] offset:32768
	ds_write_b128 v153, v[100:103]
	v_exp_f32_e32 v33, v33
	v_exp_f32_e32 v157, v34
	v_exp_f32_e32 v158, v35
	v_exp_f32_e32 v159, v36
	v_exp_f32_e32 v160, v37
	v_exp_f32_e32 v161, v38
	v_exp_f32_e32 v162, v39
	v_exp_f32_e32 v163, v40
	v_exp_f32_e32 v164, v41
	v_exp_f32_e32 v165, v42
	v_exp_f32_e32 v166, v43
	v_exp_f32_e32 v167, v44
	v_exp_f32_e32 v168, v45
	v_exp_f32_e32 v169, v46
	v_exp_f32_e32 v170, v47
	v_exp_f32_e32 v171, v48
	s_waitcnt lgkmcnt(0)
	s_barrier
	ds_read_b128 v[34:37], v150 offset:32768
	ds_read_b128 v[108:111], v150 offset:36864
	v_mov_b64_e32 v[80:81], s[18:19]
	v_mov_b64_e32 v[78:79], s[16:17]
	v_mov_b64_e32 v[76:77], s[14:15]
	v_mov_b64_e32 v[74:75], s[12:13]
	v_mov_b64_e32 v[72:73], s[10:11]
	v_mov_b64_e32 v[70:71], s[8:9]
	v_mov_b64_e32 v[68:69], s[6:7]
	v_mov_b64_e32 v[66:67], s[4:5]
	v_exp_f32_e32 v32, v32
	s_waitcnt lgkmcnt(1)
	v_mfma_f32_32x32x16_bf16 v[50:65], v[34:37], v[124:127], v[66:81]
	s_waitcnt lgkmcnt(0)
	v_mfma_f32_32x32x16_bf16 v[34:49], v[108:111], v[124:127], v[66:81]
	s_nop 6
	ds_read_b128 v[66:69], v148 offset:32768
	ds_read_b128 v[70:73], v148 offset:36864
	v_exp_f32_e32 v80, v87
	v_exp_f32_e32 v81, v88
	v_exp_f32_e32 v87, v92
	v_exp_f32_e32 v88, v93
	v_exp_f32_e32 v92, v107
	s_waitcnt lgkmcnt(1)
	v_mfma_f32_32x32x16_bf16 v[50:65], v[66:69], v[120:123], v[50:65]
	s_waitcnt lgkmcnt(0)
	v_mfma_f32_32x32x16_bf16 v[34:49], v[70:73], v[120:123], v[34:49]
	ds_read_b128 v[66:69], v147 offset:32768
	ds_read_b128 v[70:73], v147 offset:36864
	s_waitcnt lgkmcnt(1)
	v_mfma_f32_32x32x16_bf16 v[50:65], v[66:69], v[116:119], v[50:65]
	s_waitcnt lgkmcnt(0)
	v_mfma_f32_32x32x16_bf16 v[34:49], v[70:73], v[116:119], v[34:49]
	ds_read_b128 v[66:69], v146 offset:32768
	ds_read_b128 v[70:73], v146 offset:36864
	s_waitcnt lgkmcnt(1)
	v_mfma_f32_32x32x16_bf16 v[50:65], v[66:69], v[112:115], v[50:65]
	v_add_f32_e32 v66, 0, v33
	v_add_f32_e32 v66, v66, v157
	v_add_f32_e32 v66, v66, v158
	v_add_f32_e32 v66, v66, v159
	v_add_f32_e32 v66, v66, v160
	v_add_f32_e32 v66, v66, v161
	v_add_f32_e32 v66, v66, v162
	v_add_f32_e32 v66, v66, v163
	v_add_f32_e32 v66, v66, v164
	v_add_f32_e32 v66, v66, v165
	v_add_f32_e32 v66, v66, v166
	v_add_f32_e32 v66, v66, v167
	v_add_f32_e32 v66, v66, v168
	s_waitcnt lgkmcnt(0)
	v_mfma_f32_32x32x16_bf16 v[34:49], v[70:73], v[112:115], v[34:49]
	v_exp_f32_e32 v70, v83
	v_add_f32_e32 v66, v66, v169
	v_exp_f32_e32 v71, v84
	v_add_f32_e32 v66, v66, v170
	v_exp_f32_e32 v72, v85
	v_add_f32_e32 v66, v66, v171
	v_exp_f32_e32 v73, v86
	v_add_f32_e32 v66, v32, v66
	v_add_f32_e32 v66, v70, v66
	v_add_f32_e32 v66, v71, v66
	v_exp_f32_e32 v84, v89
	v_add_f32_e32 v66, v72, v66
	v_exp_f32_e32 v85, v90
	v_add_f32_e32 v66, v73, v66
	v_exp_f32_e32 v86, v91
	v_add_f32_e32 v66, v80, v66
	v_add_f32_e32 v66, v81, v66
	v_add_f32_e32 v66, v84, v66
	v_exp_f32_e32 v89, v94
	v_add_f32_e32 v66, v85, v66
	v_exp_f32_e32 v90, v95
	v_add_f32_e32 v66, v86, v66
	v_exp_f32_e32 v91, v106
	v_add_f32_e32 v66, v87, v66
	v_add_f32_e32 v66, v88, v66
	v_add_f32_e32 v66, v89, v66
	v_add_f32_e32 v66, v90, v66
	v_add_f32_e32 v66, v91, v66
	v_add_f32_e32 v83, v66, v92
	v_mov_b32_e32 v106, v83
	v_cvt_pk_bf16_f32 v66, v33, v157
	v_cvt_pk_bf16_f32 v67, v158, v159
	v_cvt_pk_bf16_f32 v68, v160, v161
	v_cvt_pk_bf16_f32 v69, v162, v163
	v_cvt_pk_bf16_f32 v74, v164, v165
	v_cvt_pk_bf16_f32 v75, v166, v167
	v_cvt_pk_bf16_f32 v76, v168, v169
	v_cvt_pk_bf16_f32 v77, v170, v171
	v_cvt_pk_bf16_f32 v78, v32, v70
	v_cvt_pk_bf16_f32 v79, v71, v72
	v_cvt_pk_bf16_f32 v80, v73, v80
	v_cvt_pk_bf16_f32 v81, v81, v84
	v_cvt_pk_bf16_f32 v70, v85, v86
	v_cvt_pk_bf16_f32 v71, v87, v88
	v_cvt_pk_bf16_f32 v72, v89, v90
	v_cvt_pk_bf16_f32 v73, v91, v92
	s_nop 1
	v_permlane32_swap_b32_e32 v83, v106
	v_permlane32_swap_b32_e32 v66, v68
	v_permlane32_swap_b32_e32 v67, v69
	v_permlane32_swap_b32_e32 v74, v76
	v_permlane32_swap_b32_e32 v75, v77
	v_permlane32_swap_b32_e32 v78, v80
	v_permlane32_swap_b32_e32 v79, v81
	v_permlane32_swap_b32_e32 v70, v72
	v_permlane32_swap_b32_e32 v71, v73
	s_cmp_lt_i32 s87, s89
	s_cselect_b64 s[72:73], -1, 0
	s_cmp_ge_i32 s87, s89
	s_cbranch_scc1 .LBB0_844
	s_add_i32 s3, s97, 64
	v_mad_i64_i32 v[32:33], s[20:21], s3, v237, v[134:135]
	v_mad_i64_i32 v[84:85], s[20:21], s3, v237, v[136:137]
	global_load_dwordx4 v[96:99], v[32:33], off offset:1024
	global_load_dwordx4 v[100:103], v[84:85], off offset:1280
